# k50 + POST token loop: 18 provably redundant s_waitcnt lgkmcnt(0) removed
# speedup vs baseline: 1.0014x; 1.0014x over previous
; #define LAS __attribute__((address_space(3)))
; DI unsigned pk2(float lo, float hi) { f32x2 x = {lo, hi}; return __builtin_bit_cast(unsigned, __builtin_convertvector(x, bf16x2_t)); }
; DI float sum32(float v) { v += __shfl_xor(v, 16); return sum16(v); }
; DI f32x2 unpk(unsigned w) { f32x2 r = {bflo(w), bfhi(w)}; return r; }
; template <int HP> DI void rope2(f32x2& x, int hl, const LAS f32x2* cs) {
;   const float pa = __shfl_xor(x[0], HP), pb = __shfl_xor(x[1], HP);
;   if (hl < HP) { const f32x2 c0 = cs[2 * hl], c1 = cs[2 * hl + 1]; x[0] = x[0] * c0[0] - pa * c0[1]; x[1] = x[1] * c1[0] - pb * c1[1]; }
;   else if (hl < 2 * HP) { const f32x2 c0 = cs[2 * (hl - HP)], c1 = cs[2 * (hl - HP) + 1]; x[0] = x[0] * c0[0] + pa * c0[1]; x[1] = x[1] * c1[0] + pb * c1[1]; }
; }
; DI void post_unit(const Params& p, int l, int unit, LAS unsigned char* lds) {
;     ...
;   for (int tp = 0; tp < 4; ++tp) {
;     constexpr int segcol[16] = {C_QA, C_QA + 128, C_KA, C_QI, C_QI + 128, C_QI + 256, C_QI + 384, C_KI, C_QB, C_QB + 128, C_KB, C_KB + 128, C_QC, C_QC + 128, C_KC, C_KC + 128};
;     unsigned raw2[2][16];
; #pragma unroll
;     for (int hf = 0; hf < 2; ++hf) { const u16* rowl = proj + (tok0 + w * 8 + 2 * tp + hf) * NP;
; #pragma unroll
;       for (int s = 0; s < 16; ++s) raw2[hf][s] = *(const unsigned*)(rowl + segcol[s] + 2 * lane); }
; #pragma unroll
;     for (int hf = 0; hf < 2; ++hf) {
;     const int t = w * 8 + 2 * tp + hf; u16* row = proj + (tok0 + t) * NP;
; #pragma unroll
;     for (int s = 0; s < 16; ++s) {
;       f32x2 x = unpk(raw2[hf][s]); u16* pp = row + segcol[s] + 2 * lane;
;       if (s < 2) {
;         const float rs = rsqrtf(sum32(x[0] * x[0] + x[1] * x[1]) * (1.0f / 64.0f) + EPS);
;         x[0] *= rs * qna[2 * hl]; x[1] *= rs * qna[2 * hl + 1]; rope2<4>(x, hl, cs16 + t * 8);
;         x *= LOG2E * 0.125f; *(unsigned*)pp = pk2(x[0], x[1]);
.LBB0_150:
	ds_read_b128 v[208:211], v35
	ds_read_b128 v[212:215], v35 offset:64
	ds_read_b128 v[216:219], v39
	ds_read_b128 v[220:223], v39 offset:256
	ds_read_b128 v[224:227], v40
	ds_read_b128 v[228:231], v40 offset:32
	ds_read_b128 v[232:235], v35 offset:128
	ds_read_b128 v[236:239], v39 offset:512
	ds_read_b128 v[240:243], v40 offset:64
	s_waitcnt lgkmcnt(0)
	s_orn2_b64 s[98:99], s[14:15], s[12:13]
	s_orn2_b64 s[100:101], s[8:9], s[6:7]
	v_cndmask_b32_e64 v80, v212, v208, s[12:13]
	v_cndmask_b32_e64 v80, 1.0, v80, s[98:99]
	v_cndmask_b32_e64 v81, v214, v210, s[12:13]
	v_cndmask_b32_e64 v81, 1.0, v81, s[98:99]
	v_cndmask_b32_e64 v82, -v213, v209, s[12:13]
	v_cndmask_b32_e64 v82, 0, v82, s[98:99]
	v_cndmask_b32_e64 v83, -v215, v211, s[12:13]
	v_cndmask_b32_e64 v83, 0, v83, s[98:99]
	v_cndmask_b32_e64 v84, v220, v216, s[10:11]
	v_cndmask_b32_e64 v85, v222, v218, s[10:11]
	v_cndmask_b32_e64 v86, -v221, v217, s[10:11]
	v_cndmask_b32_e64 v87, -v223, v219, s[10:11]
	v_cndmask_b32_e64 v88, v228, v224, s[6:7]
	v_cndmask_b32_e64 v88, 1.0, v88, s[100:101]
	v_cndmask_b32_e64 v89, v230, v226, s[6:7]
	v_cndmask_b32_e64 v89, 1.0, v89, s[100:101]
	v_cndmask_b32_e64 v90, -v229, v225, s[6:7]
	v_cndmask_b32_e64 v90, 0, v90, s[100:101]
	v_cndmask_b32_e64 v91, -v231, v227, s[6:7]
	v_cndmask_b32_e64 v91, 0, v91, s[100:101]
	v_cndmask_b32_e64 v92, v232, v212, s[12:13]
	v_cndmask_b32_e64 v92, 1.0, v92, s[98:99]
	v_cndmask_b32_e64 v93, v234, v214, s[12:13]
	v_cndmask_b32_e64 v93, 1.0, v93, s[98:99]
	v_cndmask_b32_e64 v94, -v233, v213, s[12:13]
	v_cndmask_b32_e64 v94, 0, v94, s[98:99]
	v_cndmask_b32_e64 v95, -v235, v215, s[12:13]
	v_cndmask_b32_e64 v95, 0, v95, s[98:99]
	v_cndmask_b32_e64 v96, v240, v228, s[6:7]
	v_cndmask_b32_e64 v96, 1.0, v96, s[100:101]
	v_cndmask_b32_e64 v97, v242, v230, s[6:7]
	v_cndmask_b32_e64 v97, 1.0, v97, s[100:101]
	v_cndmask_b32_e64 v98, -v241, v229, s[6:7]
	v_cndmask_b32_e64 v98, 0, v98, s[100:101]
	v_cndmask_b32_e64 v99, -v243, v231, s[6:7]
	v_cndmask_b32_e64 v99, 0, v99, s[100:101]
	v_lshl_add_u64 v[18:19], v[12:13], 0, v[0:1]
	v_add_co_u32_e32 v20, vcc, 0xa000000, v18
	s_mov_b32 s2, 0xa001000
	v_addc_co_u32_e32 v21, vcc, 0, v19, vcc
	global_load_dword v49, v[20:21], off
	v_add_co_u32_e32 v22, vcc, s2, v18
	s_mov_b32 s2, 0xa003000
	s_nop 0
	v_addc_co_u32_e32 v23, vcc, 0, v19, vcc
	v_add_co_u32_e32 v42, vcc, s77, v18
	global_load_dword v59, v[20:21], off offset:512
	global_load_dword v70, v[20:21], off offset:768
	global_load_dword v69, v[20:21], off offset:1024
	global_load_dword v68, v[20:21], off offset:1280
	global_load_dword v67, v[20:21], off offset:1536
	global_load_dword v58, v[20:21], off offset:1792
	global_load_dword v71, v[20:21], off offset:256
	v_addc_co_u32_e32 v43, vcc, 0, v19, vcc
	global_load_dword v56, v[20:21], off offset:2432
	global_load_dword v66, v[20:21], off offset:2688
	global_load_dword v65, v[20:21], off offset:2944
	global_load_dword v64, v[20:21], off offset:3200
	global_load_dword v54, v[22:23], off offset:384
	global_load_dword v63, v[22:23], off offset:640
	global_load_dword v62, v[22:23], off offset:896
	global_load_dword v61, v[22:23], off offset:1152
	v_add_co_u32_e32 v20, vcc, s2, v18
	global_load_dword v60, v[42:43], off offset:512
	global_load_dword v57, v[42:43], off offset:768
	global_load_dword v55, v[42:43], off offset:1024
	global_load_dword v53, v[42:43], off offset:1280
	global_load_dword v52, v[42:43], off offset:1536
	global_load_dword v51, v[42:43], off offset:1792
	global_load_dword v50, v[42:43], off offset:2048
	global_load_dword v48, v[42:43], off offset:2304
	v_addc_co_u32_e32 v21, vcc, 0, v19, vcc
	global_load_dword v47, v[42:43], off offset:2944
	global_load_dword v46, v[42:43], off offset:3200
	global_load_dword v45, v[42:43], off offset:3456
	global_load_dword v44, v[42:43], off offset:3712
	s_nop 0
	global_load_dword v43, v[20:21], off offset:896
	global_load_dword v42, v[20:21], off offset:1152
	global_load_dword v41, v[20:21], off offset:1408
	global_load_dword v3, v[20:21], off offset:1664
	s_waitcnt vmcnt(31)
	v_and_b32_e32 v21, 0xffff0000, v49
	v_lshlrev_b32_e32 v20, 16, v49
	v_mul_f32_e32 v22, v20, v20
	v_fmac_f32_e32 v22, v21, v21
	v_mov_b32_e32 v23, v22
	s_nop 1
	v_permlane16_swap_b32_e32 v22, v23
	v_add_f32_e32 v22, v22, v23
	s_nop 1
	v_add_f32_dpp v22, v22, v22 row_ror:8 row_mask:0xf bank_mask:0xf
	s_nop 1
	v_add_f32_dpp v22, v22, v22 row_ror:4 row_mask:0xf bank_mask:0xf
	s_nop 1
	v_add_f32_dpp v22, v22, v22 quad_perm:[2,3,0,1] row_mask:0xf bank_mask:0xf
	s_nop 1
	v_add_f32_dpp v22, v22, v22 quad_perm:[1,0,3,2] row_mask:0xf bank_mask:0xf
	v_fmamk_f32 v22, v22, 0x3c800000, v170
	v_rsq_f32_e32 v22, v22
	s_nop 0
	v_pk_mul_f32 v[22:23], v[4:5], v[22:23] op_sel_hi:[1,0]
	s_nop 0
	v_pk_mul_f32 v[22:23], v[22:23], v[20:21]
	ds_bpermute_b32 v20, v28, v22
	ds_bpermute_b32 v21, v28, v23
	v_add_u32_e32 v49, 0, v35
	s_waitcnt lgkmcnt(0)
; #define LAS __attribute__((address_space(3)))
; DI unsigned pk2(float lo, float hi) { f32x2 x = {lo, hi}; return __builtin_bit_cast(unsigned, __builtin_convertvector(x, bf16x2_t)); }
; DI float sum32(float v) { v += __shfl_xor(v, 16); return sum16(v); }
; DI float sum64(float v) { v += __shfl_xor(v, 32); return sum32(v); }
; DI f32x2 unpk(unsigned w) { f32x2 r = {bflo(w), bfhi(w)}; return r; }
; DI void post_unit(const Params& p, int l, int unit, LAS unsigned char* lds) {
;     ...
;     for (int s = 0; s < 16; ++s) {
;       f32x2 x = unpk(raw2[hf][s]); u16* pp = row + segcol[s] + 2 * lane;
;       if (s < 2) {
;         const float rs = rsqrtf(sum32(x[0] * x[0] + x[1] * x[1]) * (1.0f / 64.0f) + EPS);
;         x[0] *= rs * qna[2 * hl]; x[1] *= rs * qna[2 * hl + 1]; rope2<4>(x, hl, cs16 + t * 8);
;         x *= LOG2E * 0.125f; *(unsigned*)pp = pk2(x[0], x[1]);
;       } else if (s == 2) {
;         const float rs = rsqrtf(sum64(x[0] * x[0] + x[1] * x[1]) * (1.0f / 128.0f) + EPS);
;         *(LAS unsigned*)(At + t * 272 + lane * 4) = pk2(x[0] * rs, x[1] * rs);
;       } else if (s < 7) {
;         rope2<4>(x, hl, cs16 + t * 8); *(unsigned*)pp = pk2(x[0], x[1]);
;       } else if (s == 7) {
;         const float rs = rsqrtf(sum32(x[0] * x[0] + x[1] * x[1]) * (1.0f / 64.0f) + EPS);
;         x *= rs; rope2<4>(x, hl, cs16 + t * 8); if (lane < 32) *(unsigned*)((u16*)(p.ws + WS_KIC) + (tok0 + t) * 64 + 2 * lane) = pk2(x[0], x[1]);
	v_mul_f32_e32 v22, v80, v22
	v_mul_f32_e32 v23, v81, v23
	v_fmac_f32_e32 v22, v82, v20
	v_fmac_f32_e32 v23, v83, v21
	s_mov_b64 s[2:3], 0xa000000
	v_lshl_add_u64 v[20:21], v[18:19], 0, s[2:3]
	s_mov_b32 s2, 0x3e38aa3b
	v_pk_mul_f32 v[22:23], v[22:23], s[2:3] op_sel_hi:[1,0]
	s_nop 0
	v_cvt_pk_bf16_f32 v22, v22, v23
	global_store_dword v[20:21], v22, off
	s_waitcnt vmcnt(25)
	v_and_b32_e32 v21, 0xffff0000, v71
	v_lshlrev_b32_e32 v20, 16, v71
	v_mul_f32_e32 v22, v20, v20
	v_fmac_f32_e32 v22, v21, v21
	v_mov_b32_e32 v23, v22
	s_nop 1
	v_permlane16_swap_b32_e32 v22, v23
	v_add_f32_e32 v22, v22, v23
	s_nop 1
	v_add_f32_dpp v22, v22, v22 row_ror:8 row_mask:0xf bank_mask:0xf
	s_nop 1
	v_add_f32_dpp v22, v22, v22 row_ror:4 row_mask:0xf bank_mask:0xf
	s_nop 1
	v_add_f32_dpp v22, v22, v22 quad_perm:[2,3,0,1] row_mask:0xf bank_mask:0xf
	s_nop 1
	v_add_f32_dpp v22, v22, v22 quad_perm:[1,0,3,2] row_mask:0xf bank_mask:0xf
	v_fmamk_f32 v22, v22, 0x3c800000, v170
	v_rsq_f32_e32 v22, v22
	s_nop 0
	v_pk_mul_f32 v[22:23], v[4:5], v[22:23] op_sel_hi:[1,0]
	s_nop 0
	v_pk_mul_f32 v[22:23], v[22:23], v[20:21]
	ds_bpermute_b32 v20, v28, v22
	ds_bpermute_b32 v21, v28, v23
	s_waitcnt lgkmcnt(0)
	v_mul_f32_e32 v22, v80, v22
	v_mul_f32_e32 v23, v81, v23
	v_fmac_f32_e32 v22, v82, v20
	v_fmac_f32_e32 v23, v83, v21
	s_mov_b64 s[2:3], 0xa000100
	v_lshl_add_u64 v[20:21], v[18:19], 0, s[2:3]
	s_mov_b32 s2, 0x3e38aa3b
	v_pk_mul_f32 v[22:23], v[22:23], s[2:3] op_sel_hi:[1,0]
	s_nop 0
	v_cvt_pk_bf16_f32 v22, v22, v23
	global_store_dword v[20:21], v22, off
	v_lshlrev_b32_e32 v20, 16, v59
	v_and_b32_e32 v21, 0xffff0000, v59
	v_pk_mul_f32 v[22:23], v[20:21], v[20:21]
	v_add_u32_e32 v59, 0, v33
	v_add_f32_e32 v22, v22, v23
	v_mov_b32_e32 v23, v22
	s_nop 1
	v_permlane32_swap_b32_e32 v22, v23
	v_add_f32_e32 v22, v22, v23
	v_mov_b32_e32 v23, v22
	s_nop 1
	v_permlane16_swap_b32_e32 v22, v23
	v_add_f32_e32 v22, v22, v23
	s_nop 1
	v_add_f32_dpp v22, v22, v22 row_ror:8 row_mask:0xf bank_mask:0xf
	s_nop 1
	v_add_f32_dpp v22, v22, v22 row_ror:4 row_mask:0xf bank_mask:0xf
	s_nop 1
	v_add_f32_dpp v22, v22, v22 quad_perm:[2,3,0,1] row_mask:0xf bank_mask:0xf
	s_nop 1
	v_add_f32_dpp v22, v22, v22 quad_perm:[1,0,3,2] row_mask:0xf bank_mask:0xf
	v_fmamk_f32 v22, v22, 0x3c000000, v170
	v_rsq_f32_e32 v22, v22
	s_nop 0
	v_pk_mul_f32 v[20:21], v[22:23], v[20:21] op_sel_hi:[0,1]
	v_cvt_pk_bf16_f32 v20, v20, v21
	ds_write_b32 v59, v20
	v_lshlrev_b32_e32 v20, 16, v70
	v_and_b32_e32 v21, 0xffff0000, v70
	ds_bpermute_b32 v70, v28, v20
	ds_bpermute_b32 v23, v28, v21
	s_waitcnt lgkmcnt(0)
	v_mul_f32_e32 v20, v80, v20
	v_mul_f32_e32 v21, v81, v21
	v_fmac_f32_e32 v20, v82, v70
	v_fmac_f32_e32 v21, v83, v23
	s_mov_b64 s[2:3], 0xa000300
	v_lshl_add_u64 v[22:23], v[18:19], 0, s[2:3]
	v_cvt_pk_bf16_f32 v20, v20, v21
	global_store_dword v[22:23], v20, off
	v_lshlrev_b32_e32 v20, 16, v69
	v_and_b32_e32 v21, 0xffff0000, v69
	ds_bpermute_b32 v69, v28, v20
	ds_bpermute_b32 v23, v28, v21
	s_waitcnt lgkmcnt(0)
	v_mul_f32_e32 v20, v80, v20
	v_mul_f32_e32 v21, v81, v21
	v_fmac_f32_e32 v20, v82, v69
	v_fmac_f32_e32 v21, v83, v23
	s_mov_b64 s[2:3], 0xa000400
	v_lshl_add_u64 v[22:23], v[18:19], 0, s[2:3]
	v_cvt_pk_bf16_f32 v20, v20, v21
	global_store_dword v[22:23], v20, off
	v_lshlrev_b32_e32 v20, 16, v68
	v_and_b32_e32 v21, 0xffff0000, v68
	ds_bpermute_b32 v68, v28, v20
	ds_bpermute_b32 v23, v28, v21
	s_waitcnt lgkmcnt(0)
	v_mul_f32_e32 v20, v80, v20
	v_mul_f32_e32 v21, v81, v21
	v_fmac_f32_e32 v20, v82, v68
	v_fmac_f32_e32 v21, v83, v23
	s_mov_b64 s[2:3], 0xa000500
	v_lshl_add_u64 v[22:23], v[18:19], 0, s[2:3]
	v_cvt_pk_bf16_f32 v20, v20, v21
	global_store_dword v[22:23], v20, off
	v_lshlrev_b32_e32 v20, 16, v67
	v_and_b32_e32 v21, 0xffff0000, v67
	ds_bpermute_b32 v67, v28, v20
	ds_bpermute_b32 v23, v28, v21
	s_waitcnt lgkmcnt(0)
	v_mul_f32_e32 v20, v80, v20
	v_mul_f32_e32 v21, v81, v21
	v_fmac_f32_e32 v20, v82, v67
	v_fmac_f32_e32 v21, v83, v23
	s_mov_b64 s[2:3], 0xa000600
	v_lshl_add_u64 v[22:23], v[18:19], 0, s[2:3]
	v_cvt_pk_bf16_f32 v20, v20, v21
	global_store_dword v[22:23], v20, off
	v_lshlrev_b32_e32 v20, 16, v58
	v_and_b32_e32 v21, 0xffff0000, v58
	v_mul_f32_e32 v22, v20, v20
	v_fmac_f32_e32 v22, v21, v21
	v_mov_b32_e32 v23, v22
	s_nop 1
	v_permlane16_swap_b32_e32 v22, v23
	v_add_f32_e32 v22, v22, v23
	s_nop 1
	v_add_f32_dpp v22, v22, v22 row_ror:8 row_mask:0xf bank_mask:0xf
	s_nop 1
	v_add_f32_dpp v22, v22, v22 row_ror:4 row_mask:0xf bank_mask:0xf
	s_nop 1
	v_add_f32_dpp v22, v22, v22 quad_perm:[2,3,0,1] row_mask:0xf bank_mask:0xf
	s_nop 1
	v_add_f32_dpp v22, v22, v22 quad_perm:[1,0,3,2] row_mask:0xf bank_mask:0xf
	v_fmamk_f32 v22, v22, 0x3c800000, v170
	v_rsq_f32_e32 v22, v22
	s_nop 0
	v_pk_mul_f32 v[20:21], v[22:23], v[20:21] op_sel_hi:[0,1]
	ds_bpermute_b32 v22, v28, v20
	ds_bpermute_b32 v23, v28, v21
	s_and_saveexec_b64 s[2:3], s[12:13]
	s_xor_b64 s[18:19], exec, s[2:3]
	s_cbranch_execz .LBB0_314
	s_and_saveexec_b64 s[30:31], s[14:15]
	s_cbranch_execz .LBB0_189
	s_waitcnt lgkmcnt(0)
	v_mul_f32_e32 v20, v20, v208
	v_mul_f32_e32 v21, v210, v21
	v_fmac_f32_e32 v20, v209, v22
	v_fmac_f32_e32 v21, v211, v23

; DI unsigned pk2(float lo, float hi) { f32x2 x = {lo, hi}; return __builtin_bit_cast(unsigned, __builtin_convertvector(x, bf16x2_t)); }
; DI float sum16(float v) { v += __shfl_xor(v, 8); v += __shfl_xor(v, 4); v += __shfl_xor(v, 2); v += __shfl_xor(v, 1); return v; }
; DI void post_unit(const Params& p, int l, int unit, LAS unsigned char* lds) {
;     ...
;       } else if (s < 12) {
;         rope2<16>(x, hl, cs64 + t * 32);
;         const int hd = ((s & 1) ? 2 : 0) + hsel;
;         const float lg = log1pf(-exp2f(-5.0f - (float)hd));
;         const float f = (s < 10) ? expf(lg * (float)(t + 1)) : expf(lg * (float)(63 - t)) * 0.125f;
;         x *= f; *(unsigned*)pp = pk2(x[0], x[1]);
;       } else {
;         const float* gn = (s < 14) ? qnc : knc;
;         const float rs = rsqrtf(sum16(x[0] * x[0] + x[1] * x[1]) * (1.0f / 32.0f) + EPS);
;         x[0] *= rs * gn[2 * hl16]; x[1] *= rs * gn[2 * hl16 + 1]; rope2<2>(x, hl16, cs8 + t * 4);
;         if (s < 14) x *= LOG2E * 0.17677669529663687f;
;         *(unsigned*)pp = pk2(x[0], x[1]);
.LBB0_196:
	s_or_b64 exec, exec, s[18:19]
	v_add_u32_e32 v58, s36, v2
	s_waitcnt lgkmcnt(1)
	v_add_u32_e32 v67, 1, v58
	v_cvt_f32_i32_e32 v67, v67
	s_mov_b64 s[2:3], 0xa000980
	s_waitcnt lgkmcnt(0)
	v_lshl_add_u64 v[22:23], v[18:19], 0, s[2:3]
	v_mul_f32_e32 v68, v31, v67
	v_mul_f32_e32 v69, 0x3fb8aa3b, v68
	v_fma_f32 v70, v68, s64, -v69
	v_rndne_f32_e32 v71, v69
	v_fmac_f32_e32 v70, 0x32a5705f, v68
	v_sub_f32_e32 v69, v69, v71
	v_add_f32_e32 v69, v69, v70
	v_exp_f32_e32 v69, v69
	v_cvt_i32_f32_e32 v70, v71
	v_cmp_ngt_f32_e32 vcc, s65, v68
	v_ldexp_f32 v69, v69, v70
	s_nop 0
	v_cndmask_b32_e32 v69, 0, v69, vcc
	v_cmp_nlt_f32_e32 vcc, s89, v68
	s_nop 1
	v_cndmask_b32_e32 v68, v177, v69, vcc
	v_pk_mul_f32 v[20:21], v[68:69], v[20:21] op_sel_hi:[0,1]
	v_cvt_pk_bf16_f32 v20, v20, v21
	global_store_dword v[22:23], v20, off
	s_waitcnt vmcnt(29)
	v_lshlrev_b32_e32 v68, 16, v66
	v_and_b32_e32 v20, 0xffff0000, v66
	ds_bpermute_b32 v66, v26, v68
	ds_bpermute_b32 v21, v26, v20
	s_waitcnt lgkmcnt(0)
	v_mul_f32_e32 v22, v84, v68
	v_mul_f32_e32 v23, v85, v20
	v_fmac_f32_e32 v22, v86, v66
	v_fmac_f32_e32 v23, v87, v21
	s_waitcnt lgkmcnt(1)
	v_mul_f32_e32 v66, v32, v67
	v_mul_f32_e32 v67, 0x3fb8aa3b, v66
	v_fma_f32 v68, v66, s64, -v67
	v_rndne_f32_e32 v69, v67
	v_fmac_f32_e32 v68, 0x32a5705f, v66
	v_sub_f32_e32 v67, v67, v69
	v_add_f32_e32 v67, v67, v68
	v_exp_f32_e32 v67, v67
	v_cvt_i32_f32_e32 v68, v69
	v_cmp_ngt_f32_e32 vcc, s65, v66
	s_mov_b64 s[2:3], 0xa000a80
	v_lshl_add_u64 v[20:21], v[18:19], 0, s[2:3]
	v_ldexp_f32 v67, v67, v68
	v_cndmask_b32_e32 v67, 0, v67, vcc
	v_cmp_nlt_f32_e32 vcc, s89, v66
	s_nop 1
	v_cndmask_b32_e32 v66, v177, v67, vcc
	v_pk_mul_f32 v[22:23], v[66:67], v[22:23] op_sel_hi:[0,1]
	v_cvt_pk_bf16_f32 v22, v22, v23
	global_store_dword v[20:21], v22, off
	s_waitcnt vmcnt(29)
	v_lshlrev_b32_e32 v66, 16, v65
	v_and_b32_e32 v22, 0xffff0000, v65
	ds_bpermute_b32 v65, v26, v66
	ds_bpermute_b32 v23, v26, v22
	s_waitcnt lgkmcnt(0)
	v_mul_f32_e32 v20, v84, v66
	v_mul_f32_e32 v21, v85, v22
	v_fmac_f32_e32 v20, v86, v65
	v_fmac_f32_e32 v21, v87, v23
	s_waitcnt lgkmcnt(1)
	v_add_u32_e32 v65, 1, v38
	v_cvt_f32_i32_e32 v65, v65
	s_mov_b64 s[2:3], 0xa000b80
	v_lshl_add_u64 v[22:23], v[18:19], 0, s[2:3]
	v_mul_f32_e32 v66, v31, v65
	v_mul_f32_e32 v67, 0x3fb8aa3b, v66
	v_fma_f32 v68, v66, s64, -v67
	v_rndne_f32_e32 v69, v67
	v_fmac_f32_e32 v68, 0x32a5705f, v66
	v_sub_f32_e32 v67, v67, v69
	v_add_f32_e32 v67, v67, v68
	v_exp_f32_e32 v67, v67
	v_cvt_i32_f32_e32 v68, v69
	v_cmp_ngt_f32_e32 vcc, s65, v66
	v_ldexp_f32 v67, v67, v68
	s_nop 0
	v_cndmask_b32_e32 v67, 0, v67, vcc
	v_cmp_nlt_f32_e32 vcc, s89, v66
	s_nop 1
	v_cndmask_b32_e32 v66, v177, v67, vcc
	v_mul_f32_e32 v66, 0x3e000000, v66
	v_pk_mul_f32 v[20:21], v[66:67], v[20:21] op_sel_hi:[0,1]
	v_cvt_pk_bf16_f32 v20, v20, v21
	global_store_dword v[22:23], v20, off
	s_waitcnt vmcnt(29)
	v_lshlrev_b32_e32 v66, 16, v64
	v_and_b32_e32 v20, 0xffff0000, v64
	ds_bpermute_b32 v64, v26, v66
	ds_bpermute_b32 v21, v26, v20
	s_waitcnt lgkmcnt(0)
	v_mul_f32_e32 v22, v84, v66
	v_mul_f32_e32 v23, v85, v20
	v_fmac_f32_e32 v22, v86, v64
	v_fmac_f32_e32 v23, v87, v21
	s_waitcnt lgkmcnt(1)
	v_mul_f32_e32 v64, v32, v65
	v_mul_f32_e32 v65, 0x3fb8aa3b, v64
	v_fma_f32 v66, v64, s64, -v65
	v_rndne_f32_e32 v67, v65
	v_fmac_f32_e32 v66, 0x32a5705f, v64
	v_sub_f32_e32 v65, v65, v67
	v_add_f32_e32 v65, v65, v66
	v_exp_f32_e32 v65, v65
	v_cvt_i32_f32_e32 v66, v67
	v_cmp_ngt_f32_e32 vcc, s65, v64
	s_mov_b64 s[2:3], 0xa000c80
	v_lshl_add_u64 v[20:21], v[18:19], 0, s[2:3]
	v_ldexp_f32 v65, v65, v66
	v_cndmask_b32_e32 v65, 0, v65, vcc
	v_cmp_nlt_f32_e32 vcc, s89, v64
	s_nop 1
	v_cndmask_b32_e32 v64, v177, v65, vcc
	v_mul_f32_e32 v64, 0x3e000000, v64
	v_pk_mul_f32 v[22:23], v[64:65], v[22:23] op_sel_hi:[0,1]
	v_cvt_pk_bf16_f32 v22, v22, v23
	global_store_dword v[20:21], v22, off
	s_waitcnt vmcnt(29)
	v_lshlrev_b32_e32 v20, 16, v54
	v_and_b32_e32 v21, 0xffff0000, v54
	v_mul_f32_e32 v22, v20, v20
	v_fmac_f32_e32 v22, v21, v21
	s_nop 1
	v_add_f32_dpp v22, v22, v22 row_ror:8 row_mask:0xf bank_mask:0xf
	s_nop 1
	v_add_f32_dpp v22, v22, v22 row_ror:4 row_mask:0xf bank_mask:0xf
	s_nop 1
	v_add_f32_dpp v22, v22, v22 quad_perm:[2,3,0,1] row_mask:0xf bank_mask:0xf
	s_nop 1
	v_add_f32_dpp v22, v22, v22 quad_perm:[1,0,3,2] row_mask:0xf bank_mask:0xf
	v_fmamk_f32 v22, v22, 0x3d000000, v170
	v_rsq_f32_e32 v22, v22
	s_nop 0
	v_pk_mul_f32 v[22:23], v[6:7], v[22:23] op_sel_hi:[1,0]
	s_nop 0
	v_pk_mul_f32 v[22:23], v[22:23], v[20:21]
	ds_bpermute_b32 v20, v29, v22
	ds_bpermute_b32 v21, v29, v23
	v_add_u32_e32 v54, 0, v40
	s_waitcnt lgkmcnt(0)
	v_mul_f32_e32 v22, v88, v22
	v_mul_f32_e32 v23, v89, v23
	v_fmac_f32_e32 v22, v90, v20
	v_fmac_f32_e32 v23, v91, v21
	s_mov_b64 s[2:3], 0xa001180
	v_lshl_add_u64 v[20:21], v[18:19], 0, s[2:3]
	s_mov_b32 s2, 0x3e8293ee
	v_pk_mul_f32 v[22:23], v[22:23], s[2:3] op_sel_hi:[1,0]
	s_nop 0
	v_cvt_pk_bf16_f32 v22, v22, v23
	global_store_dword v[20:21], v22, off
	s_waitcnt vmcnt(29)
	v_lshlrev_b32_e32 v20, 16, v63
	v_and_b32_e32 v21, 0xffff0000, v63
	v_mul_f32_e32 v22, v20, v20
	v_fmac_f32_e32 v22, v21, v21
	s_nop 1
	v_add_f32_dpp v22, v22, v22 row_ror:8 row_mask:0xf bank_mask:0xf
	s_nop 1
	v_add_f32_dpp v22, v22, v22 row_ror:4 row_mask:0xf bank_mask:0xf
	s_nop 1
	v_add_f32_dpp v22, v22, v22 quad_perm:[2,3,0,1] row_mask:0xf bank_mask:0xf
	s_nop 1
	v_add_f32_dpp v22, v22, v22 quad_perm:[1,0,3,2] row_mask:0xf bank_mask:0xf
	v_fmamk_f32 v22, v22, 0x3d000000, v170
	v_rsq_f32_e32 v22, v22
	s_nop 0
	v_pk_mul_f32 v[22:23], v[6:7], v[22:23] op_sel_hi:[1,0]
	s_nop 0
	v_pk_mul_f32 v[22:23], v[22:23], v[20:21]
	ds_bpermute_b32 v20, v29, v22
	ds_bpermute_b32 v21, v29, v23
	s_waitcnt lgkmcnt(0)
; #define LAS __attribute__((address_space(3)))
; DI unsigned pk2(float lo, float hi) { f32x2 x = {lo, hi}; return __builtin_bit_cast(unsigned, __builtin_convertvector(x, bf16x2_t)); }
; DI float sum16(float v) { v += __shfl_xor(v, 8); v += __shfl_xor(v, 4); v += __shfl_xor(v, 2); v += __shfl_xor(v, 1); return v; }
; DI float sum32(float v) { v += __shfl_xor(v, 16); return sum16(v); }
; DI float sum64(float v) { v += __shfl_xor(v, 32); return sum32(v); }
; DI f32x2 unpk(unsigned w) { f32x2 r = {bflo(w), bfhi(w)}; return r; }
; DI void post_unit(const Params& p, int l, int unit, LAS unsigned char* lds) {
;     ...
;     for (int s = 0; s < 16; ++s) {
;       f32x2 x = unpk(raw2[hf][s]); u16* pp = row + segcol[s] + 2 * lane;
;       if (s < 2) {
;         const float rs = rsqrtf(sum32(x[0] * x[0] + x[1] * x[1]) * (1.0f / 64.0f) + EPS);
;         x[0] *= rs * qna[2 * hl]; x[1] *= rs * qna[2 * hl + 1]; rope2<4>(x, hl, cs16 + t * 8);
;         x *= LOG2E * 0.125f; *(unsigned*)pp = pk2(x[0], x[1]);
;       } else if (s == 2) {
;         const float rs = rsqrtf(sum64(x[0] * x[0] + x[1] * x[1]) * (1.0f / 128.0f) + EPS);
;         *(LAS unsigned*)(At + t * 272 + lane * 4) = pk2(x[0] * rs, x[1] * rs);
;     ...
;       } else {
;         const float* gn = (s < 14) ? qnc : knc;
;         const float rs = rsqrtf(sum16(x[0] * x[0] + x[1] * x[1]) * (1.0f / 32.0f) + EPS);
;         x[0] *= rs * gn[2 * hl16]; x[1] *= rs * gn[2 * hl16 + 1]; rope2<2>(x, hl16, cs8 + t * 4);
;         if (s < 14) x *= LOG2E * 0.17677669529663687f;
;         *(unsigned*)pp = pk2(x[0], x[1]);
	v_mul_f32_e32 v22, v88, v22
	v_mul_f32_e32 v23, v89, v23
	v_fmac_f32_e32 v22, v90, v20
	v_fmac_f32_e32 v23, v91, v21
	s_mov_b64 s[2:3], 0xa001280
	v_lshl_add_u64 v[20:21], v[18:19], 0, s[2:3]
	s_mov_b32 s2, 0x3e8293ee
	v_pk_mul_f32 v[22:23], v[22:23], s[2:3] op_sel_hi:[1,0]
	s_nop 0
	v_cvt_pk_bf16_f32 v22, v22, v23
	global_store_dword v[20:21], v22, off
	s_waitcnt vmcnt(29)
	v_lshlrev_b32_e32 v20, 16, v62
	v_and_b32_e32 v21, 0xffff0000, v62
	v_mul_f32_e32 v22, v20, v20
	v_fmac_f32_e32 v22, v21, v21
	s_nop 1
	v_add_f32_dpp v22, v22, v22 row_ror:8 row_mask:0xf bank_mask:0xf
	s_nop 1
	v_add_f32_dpp v22, v22, v22 row_ror:4 row_mask:0xf bank_mask:0xf
	s_nop 1
	v_add_f32_dpp v22, v22, v22 quad_perm:[2,3,0,1] row_mask:0xf bank_mask:0xf
	s_nop 1
	v_add_f32_dpp v22, v22, v22 quad_perm:[1,0,3,2] row_mask:0xf bank_mask:0xf
	v_fmamk_f32 v22, v22, 0x3d000000, v170
	v_rsq_f32_e32 v22, v22
	s_nop 0
	v_pk_mul_f32 v[22:23], v[8:9], v[22:23] op_sel_hi:[1,0]
	s_nop 0
	v_pk_mul_f32 v[22:23], v[22:23], v[20:21]
	ds_bpermute_b32 v20, v29, v22
	ds_bpermute_b32 v21, v29, v23
	s_waitcnt lgkmcnt(0)
	v_mul_f32_e32 v22, v88, v22
	v_mul_f32_e32 v23, v89, v23
	v_fmac_f32_e32 v22, v90, v20
	v_fmac_f32_e32 v23, v91, v21
	s_mov_b64 s[2:3], 0xa001380
	v_lshl_add_u64 v[20:21], v[18:19], 0, s[2:3]
	v_cvt_pk_bf16_f32 v22, v22, v23
	global_store_dword v[20:21], v22, off
	s_waitcnt vmcnt(29)
	v_lshlrev_b32_e32 v20, 16, v61
	v_and_b32_e32 v21, 0xffff0000, v61
	v_mul_f32_e32 v22, v20, v20
	v_fmac_f32_e32 v22, v21, v21
	s_nop 1
	v_add_f32_dpp v22, v22, v22 row_ror:8 row_mask:0xf bank_mask:0xf
	s_nop 1
	v_add_f32_dpp v22, v22, v22 row_ror:4 row_mask:0xf bank_mask:0xf
	s_nop 1
	v_add_f32_dpp v22, v22, v22 quad_perm:[2,3,0,1] row_mask:0xf bank_mask:0xf
	s_nop 1
	v_add_f32_dpp v22, v22, v22 quad_perm:[1,0,3,2] row_mask:0xf bank_mask:0xf
	v_fmamk_f32 v22, v22, 0x3d000000, v170
	v_rsq_f32_e32 v22, v22
	s_nop 0
	v_pk_mul_f32 v[22:23], v[8:9], v[22:23] op_sel_hi:[1,0]
	s_nop 0
	v_pk_mul_f32 v[22:23], v[22:23], v[20:21]
	ds_bpermute_b32 v20, v29, v22
	ds_bpermute_b32 v21, v29, v23
	s_waitcnt lgkmcnt(0)
	v_mul_f32_e32 v22, v88, v22
	v_mul_f32_e32 v23, v89, v23
	v_fmac_f32_e32 v22, v90, v20
	v_fmac_f32_e32 v23, v91, v21
	s_mov_b64 s[2:3], 0xa001480
	v_lshl_add_u64 v[18:19], v[18:19], 0, s[2:3]
	s_waitcnt lgkmcnt(1)
	v_cvt_pk_bf16_f32 v20, v22, v23
	global_store_dword v[18:19], v20, off
	s_waitcnt vmcnt(29)
	v_and_b32_e32 v19, 0xffff0000, v60
	v_lshlrev_b32_e32 v18, 16, v60
	v_mul_f32_e32 v20, v18, v18
	v_fmac_f32_e32 v20, v19, v19
	v_mov_b32_e32 v21, v20
	s_nop 1
	v_permlane16_swap_b32_e32 v20, v21
	v_add_f32_e32 v20, v20, v21
	s_nop 1
	v_add_f32_dpp v20, v20, v20 row_ror:8 row_mask:0xf bank_mask:0xf
	s_nop 1
	v_add_f32_dpp v20, v20, v20 row_ror:4 row_mask:0xf bank_mask:0xf
	s_nop 1
	v_add_f32_dpp v20, v20, v20 quad_perm:[2,3,0,1] row_mask:0xf bank_mask:0xf
	s_nop 1
	v_add_f32_dpp v20, v20, v20 quad_perm:[1,0,3,2] row_mask:0xf bank_mask:0xf
	v_fmamk_f32 v20, v20, 0x3c800000, v170
	v_rsq_f32_e32 v20, v20
	s_nop 0
	v_pk_mul_f32 v[20:21], v[4:5], v[20:21] op_sel_hi:[1,0]
	s_nop 0
	v_pk_mul_f32 v[20:21], v[20:21], v[18:19]
	ds_bpermute_b32 v18, v28, v20
	ds_bpermute_b32 v19, v28, v21
	s_waitcnt lgkmcnt(0)
	v_mul_f32_e32 v20, v92, v20
	v_mul_f32_e32 v21, v93, v21
	v_fmac_f32_e32 v20, v94, v18
	v_fmac_f32_e32 v21, v95, v19
	s_mov_b32 s2, 0x3e38aa3b
	v_lshl_add_u64 v[18:19], v[14:15], 0, v[0:1]
	v_pk_mul_f32 v[20:21], v[20:21], s[2:3] op_sel_hi:[1,0]
	s_nop 0
	v_cvt_pk_bf16_f32 v22, v20, v21
	v_add_co_u32_e32 v20, vcc, 0xa002000, v18
	s_nop 1
	v_addc_co_u32_e32 v21, vcc, 0, v19, vcc
	global_store_dword v[20:21], v22, off offset:512
	s_waitcnt vmcnt(29)
	v_and_b32_e32 v21, 0xffff0000, v57
	v_lshlrev_b32_e32 v20, 16, v57
	v_mul_f32_e32 v22, v20, v20
	v_fmac_f32_e32 v22, v21, v21
	v_mov_b32_e32 v23, v22
	s_nop 1
	v_permlane16_swap_b32_e32 v22, v23
	v_add_f32_e32 v22, v22, v23
	s_nop 1
	v_add_f32_dpp v22, v22, v22 row_ror:8 row_mask:0xf bank_mask:0xf
	s_nop 1
	v_add_f32_dpp v22, v22, v22 row_ror:4 row_mask:0xf bank_mask:0xf
	s_nop 1
	v_add_f32_dpp v22, v22, v22 quad_perm:[2,3,0,1] row_mask:0xf bank_mask:0xf
	s_nop 1
	v_add_f32_dpp v22, v22, v22 quad_perm:[1,0,3,2] row_mask:0xf bank_mask:0xf
	v_fmamk_f32 v22, v22, 0x3c800000, v170
	v_rsq_f32_e32 v22, v22
	s_nop 0
	v_pk_mul_f32 v[22:23], v[4:5], v[22:23] op_sel_hi:[1,0]
	s_nop 0
	v_pk_mul_f32 v[22:23], v[22:23], v[20:21]
	ds_bpermute_b32 v20, v28, v22
	ds_bpermute_b32 v21, v28, v23
	s_waitcnt lgkmcnt(0)
	v_mul_f32_e32 v22, v92, v22
	v_mul_f32_e32 v23, v93, v23
	v_fmac_f32_e32 v22, v94, v20
	v_fmac_f32_e32 v23, v95, v21
	s_mov_b32 s2, 0x3e38aa3b
	v_pk_mul_f32 v[20:21], v[22:23], s[2:3] op_sel_hi:[1,0]
	s_nop 0
	v_cvt_pk_bf16_f32 v22, v20, v21
	v_add_co_u32_e32 v20, vcc, 0xa002000, v18
	s_nop 1
	v_addc_co_u32_e32 v21, vcc, 0, v19, vcc
	global_store_dword v[20:21], v22, off offset:768
	s_waitcnt vmcnt(29)
	v_lshlrev_b32_e32 v20, 16, v55
	v_and_b32_e32 v21, 0xffff0000, v55
	v_mul_f32_e32 v22, v20, v20
	v_fmac_f32_e32 v22, v21, v21
	v_mov_b32_e32 v23, v22
	s_nop 1
	v_permlane32_swap_b32_e32 v22, v23
	v_add_f32_e32 v22, v22, v23
	v_mov_b32_e32 v23, v22
	s_nop 1
	v_permlane16_swap_b32_e32 v22, v23
	v_add_f32_e32 v22, v22, v23
	s_nop 1
	v_add_f32_dpp v22, v22, v22 row_ror:8 row_mask:0xf bank_mask:0xf
	s_nop 1
	v_add_f32_dpp v22, v22, v22 row_ror:4 row_mask:0xf bank_mask:0xf
	s_nop 1
	v_add_f32_dpp v22, v22, v22 quad_perm:[2,3,0,1] row_mask:0xf bank_mask:0xf
	s_nop 1
	v_add_f32_dpp v22, v22, v22 quad_perm:[1,0,3,2] row_mask:0xf bank_mask:0xf
	v_fmamk_f32 v22, v22, 0x3c000000, v170
	v_rsq_f32_e32 v22, v22
	s_nop 0
	v_pk_mul_f32 v[20:21], v[22:23], v[20:21] op_sel_hi:[0,1]
	v_cvt_pk_bf16_f32 v20, v20, v21
	ds_write_b32 v59, v20 offset:272
	s_waitcnt vmcnt(28)
	v_lshlrev_b32_e32 v20, 16, v53
	v_and_b32_e32 v21, 0xffff0000, v53
	ds_bpermute_b32 v53, v28, v20
	ds_bpermute_b32 v23, v28, v21
	s_waitcnt lgkmcnt(0)
	v_mul_f32_e32 v20, v92, v20
	v_mul_f32_e32 v21, v93, v21
	v_fmac_f32_e32 v20, v94, v53
	v_fmac_f32_e32 v21, v95, v23
	v_cvt_pk_bf16_f32 v22, v20, v21
	v_add_co_u32_e32 v20, vcc, 0xa002000, v18
	s_nop 1
	v_addc_co_u32_e32 v21, vcc, 0, v19, vcc
	global_store_dword v[20:21], v22, off offset:1280
	s_waitcnt vmcnt(28)
	v_lshlrev_b32_e32 v20, 16, v52
	v_and_b32_e32 v21, 0xffff0000, v52
	ds_bpermute_b32 v52, v28, v20
	s_waitcnt lgkmcnt(1)
	ds_bpermute_b32 v23, v28, v21
	s_and_saveexec_b64 s[2:3], s[12:13]
	s_xor_b64 s[18:19], exec, s[2:3]
	s_cbranch_execz .LBB0_254
	s_and_saveexec_b64 s[30:31], s[14:15]
	s_cbranch_execz .LBB0_253
	v_mov_b32_e32 v22, v21
	s_waitcnt lgkmcnt(0)
	v_mul_f32_e32 v20, v212, v20
	v_mul_f32_e32 v21, v214, v22
	v_fmac_f32_e32 v20, v213, v52
	v_fmac_f32_e32 v21, v215, v23

; DI unsigned pk2(float lo, float hi) { f32x2 x = {lo, hi}; return __builtin_bit_cast(unsigned, __builtin_convertvector(x, bf16x2_t)); }
; DI float sum16(float v) { v += __shfl_xor(v, 8); v += __shfl_xor(v, 4); v += __shfl_xor(v, 2); v += __shfl_xor(v, 1); return v; }
; DI void post_unit(const Params& p, int l, int unit, LAS unsigned char* lds) {
;     ...
;       } else {
;         const float* gn = (s < 14) ? qnc : knc;
;         const float rs = rsqrtf(sum16(x[0] * x[0] + x[1] * x[1]) * (1.0f / 32.0f) + EPS);
;         x[0] *= rs * gn[2 * hl16]; x[1] *= rs * gn[2 * hl16 + 1]; rope2<2>(x, hl16, cs8 + t * 4);
;         if (s < 14) x *= LOG2E * 0.17677669529663687f;
;         *(unsigned*)pp = pk2(x[0], x[1]);
.LBB0_296:
	s_or_b64 exec, exec, s[18:19]
	s_mov_b32 s2, 0x3e8293ee
	s_waitcnt lgkmcnt(0)
	v_pk_mul_f32 v[20:21], v[22:23], s[2:3] op_sel_hi:[1,0]
	s_nop 0
	v_cvt_pk_bf16_f32 v22, v20, v21
	v_add_co_u32_e32 v20, vcc, 0xa003000, v18
	s_nop 1
	v_addc_co_u32_e32 v21, vcc, 0, v19, vcc
	global_store_dword v[20:21], v22, off offset:896
	s_waitcnt vmcnt(27)
	v_lshlrev_b32_e32 v20, 16, v42
	v_and_b32_e32 v21, 0xffff0000, v42
	v_mul_f32_e32 v22, v20, v20
	v_fmac_f32_e32 v22, v21, v21
	s_nop 1
	v_add_f32_dpp v22, v22, v22 row_ror:8 row_mask:0xf bank_mask:0xf
	s_nop 1
	v_add_f32_dpp v22, v22, v22 row_ror:4 row_mask:0xf bank_mask:0xf
	s_nop 1
	v_add_f32_dpp v22, v22, v22 quad_perm:[2,3,0,1] row_mask:0xf bank_mask:0xf
	s_nop 1
	v_add_f32_dpp v22, v22, v22 quad_perm:[1,0,3,2] row_mask:0xf bank_mask:0xf
	v_fmamk_f32 v22, v22, 0x3d000000, v170
	v_rsq_f32_e32 v22, v22
	s_nop 0
	v_pk_mul_f32 v[22:23], v[6:7], v[22:23] op_sel_hi:[1,0]
	s_nop 0
	v_pk_mul_f32 v[22:23], v[22:23], v[20:21]
	ds_bpermute_b32 v20, v29, v22
	ds_bpermute_b32 v21, v29, v23
	s_waitcnt lgkmcnt(0)
	v_mul_f32_e32 v22, v96, v22
	v_mul_f32_e32 v23, v97, v23
	v_fmac_f32_e32 v22, v98, v20
	v_fmac_f32_e32 v23, v99, v21
	s_mov_b32 s2, 0x3e8293ee
	v_pk_mul_f32 v[20:21], v[22:23], s[2:3] op_sel_hi:[1,0]
	s_nop 0
	v_cvt_pk_bf16_f32 v22, v20, v21
	v_add_co_u32_e32 v20, vcc, 0xa003000, v18
	s_nop 1
	v_addc_co_u32_e32 v21, vcc, 0, v19, vcc
	global_store_dword v[20:21], v22, off offset:1152
	s_waitcnt vmcnt(27)
	v_lshlrev_b32_e32 v20, 16, v41
	v_and_b32_e32 v21, 0xffff0000, v41
	v_mul_f32_e32 v22, v20, v20
	v_fmac_f32_e32 v22, v21, v21
	s_nop 1
	v_add_f32_dpp v22, v22, v22 row_ror:8 row_mask:0xf bank_mask:0xf
	s_nop 1
	v_add_f32_dpp v22, v22, v22 row_ror:4 row_mask:0xf bank_mask:0xf
	s_nop 1
	v_add_f32_dpp v22, v22, v22 quad_perm:[2,3,0,1] row_mask:0xf bank_mask:0xf
	s_nop 1
	v_add_f32_dpp v22, v22, v22 quad_perm:[1,0,3,2] row_mask:0xf bank_mask:0xf
	v_fmamk_f32 v22, v22, 0x3d000000, v170
	v_rsq_f32_e32 v22, v22
	s_nop 0
	v_pk_mul_f32 v[22:23], v[8:9], v[22:23] op_sel_hi:[1,0]
	s_nop 0
	v_pk_mul_f32 v[22:23], v[22:23], v[20:21]
	ds_bpermute_b32 v20, v29, v22
	ds_bpermute_b32 v21, v29, v23
	s_waitcnt lgkmcnt(0)
	v_mul_f32_e32 v22, v96, v22
	v_mul_f32_e32 v23, v97, v23
	v_fmac_f32_e32 v22, v98, v20
	v_fmac_f32_e32 v23, v99, v21
	s_waitcnt lgkmcnt(1)
	v_add_co_u32_e32 v20, vcc, 0xa003000, v18
	v_cvt_pk_bf16_f32 v22, v22, v23
	v_addc_co_u32_e32 v21, vcc, 0, v19, vcc
	global_store_dword v[20:21], v22, off offset:1408
	s_waitcnt vmcnt(27)
	v_lshlrev_b32_e32 v20, 16, v3
	v_and_b32_e32 v21, 0xffff0000, v3
	v_pk_mul_f32 v[22:23], v[20:21], v[20:21]
	s_nop 0
	v_add_f32_e32 v3, v22, v23
	s_nop 1
	v_add_f32_dpp v3, v3, v3 row_ror:8 row_mask:0xf bank_mask:0xf
	s_nop 1
	v_add_f32_dpp v3, v3, v3 row_ror:4 row_mask:0xf bank_mask:0xf
	s_nop 1
	v_add_f32_dpp v3, v3, v3 quad_perm:[2,3,0,1] row_mask:0xf bank_mask:0xf
	s_nop 1
	v_add_f32_dpp v3, v3, v3 quad_perm:[1,0,3,2] row_mask:0xf bank_mask:0xf
	v_fmamk_f32 v3, v3, 0x3d000000, v170
	v_cmp_gt_f32_e32 vcc, s33, v3
	v_mul_f32_e32 v22, 0x4b800000, v3
	s_nop 0
	v_cndmask_b32_e32 v3, v3, v22, vcc
	v_rsq_f32_e32 v3, v3
	s_nop 0
	v_mul_f32_e32 v22, 0x45800000, v3
	v_cndmask_b32_e32 v22, v3, v22, vcc
	v_pk_mul_f32 v[22:23], v[8:9], v[22:23] op_sel_hi:[1,0]
	s_nop 0
	v_pk_mul_f32 v[22:23], v[22:23], v[20:21]
	ds_bpermute_b32 v3, v29, v22
	ds_bpermute_b32 v21, v29, v23
	s_and_saveexec_b64 s[2:3], s[6:7]
	s_xor_b64 s[18:19], exec, s[2:3]
	s_cbranch_execz .LBB0_312
	s_and_saveexec_b64 s[30:31], s[8:9]
	s_cbranch_execz .LBB0_311
	v_mov_b32_e32 v20, v23
	s_waitcnt lgkmcnt(0)
	v_mul_f32_e32 v22, v22, v228
	v_mul_f32_e32 v23, v20, v230
	v_fmac_f32_e32 v22, v229, v3
	v_fmac_f32_e32 v23, v21, v231
